# GEMM1 V-tile epilogue: 4x4 in-register transpose (bf16 pack + DPP), 8-byte stores instead of 2-byte
# baseline (speedup 1.0000x reference)
.LBB0_148:
	s_and_b64 vcc, exec, s[28:29]
	s_cbranch_vccz .LBB0_150
	s_lshl_b32 s16, s36, 26
	v_lshl_or_b32 v140, s35, 9, v199
	s_add_u32 s16, s58, s16
	s_waitcnt lgkmcnt(0)
	v_add_u32_e32 v156, s38, v142
	v_or_b32_e32 v182, s21, v140
	s_addc_u32 s17, s59, 0
	v_ashrrev_i32_e32 v157, 31, v156
	v_ashrrev_i32_e32 v183, 31, v182
	v_lshl_add_u64 v[180:181], v[156:157], 1, s[16:17]
	v_lshlrev_b64 v[156:157], 13, v[182:183]
	v_lshl_add_u64 v[156:157], v[180:181], 0, v[156:157]
	v_or_b32_e32 v164, 4, v182
	v_ashrrev_i32_e32 v165, 31, v164
	v_lshlrev_b64 v[164:165], 13, v[164:165]
	v_lshl_add_u64 v[164:165], v[180:181], 0, v[164:165]
	v_or_b32_e32 v172, 0x80, v182
	v_ashrrev_i32_e32 v173, 31, v172
	v_lshlrev_b64 v[172:173], 13, v[172:173]
	v_lshl_add_u64 v[172:173], v[180:181], 0, v[172:173]
	v_or_b32_e32 v182, 0x84, v182
	v_ashrrev_i32_e32 v183, 31, v182
	v_lshlrev_b64 v[182:183], 13, v[182:183]
	v_lshl_add_u64 v[180:181], v[180:181], 0, v[182:183]
	v_mbcnt_lo_u32_b32 v140, -1, 0
	v_mbcnt_hi_u32_b32 v140, -1, v140
	v_and_b32_e32 v158, 3, v140
	v_mul_u32_u24_e32 v158, 0x1ffe, v158
	v_mov_b32_e32 v159, 0
	v_and_b32_e32 v160, 1, v140
	v_cmp_ne_u32_e32 vcc, 0, v160
	v_lshl_add_u64 v[156:157], v[156:157], 0, v[158:159]
	v_lshl_add_u64 v[164:165], v[164:165], 0, v[158:159]
	v_lshl_add_u64 v[172:173], v[172:173], 0, v[158:159]
	v_lshl_add_u64 v[180:181], v[180:181], 0, v[158:159]
	v_mov_b32_e32 v161, 0x5040100
	v_mov_b32_e32 v186, 0x3020706
	v_cndmask_b32_e32 v161, v161, v186, vcc
	v_and_b32_e32 v160, 2, v140
	v_cmp_ne_u32_e32 vcc, 0, v160
	s_nop 1
	v_cvt_pk_bf16_f32 v162, v124, v125
	v_cvt_pk_bf16_f32 v163, v126, v127
	v_cvt_pk_bf16_f32 v174, v120, v121
	v_cvt_pk_bf16_f32 v175, v122, v123
	v_mov_b32_dpp v166, v162 quad_perm:[1,0,3,2] row_mask:0xf bank_mask:0xf
	v_mov_b32_dpp v167, v163 quad_perm:[1,0,3,2] row_mask:0xf bank_mask:0xf
	v_mov_b32_dpp v176, v174 quad_perm:[1,0,3,2] row_mask:0xf bank_mask:0xf
	v_mov_b32_dpp v177, v175 quad_perm:[1,0,3,2] row_mask:0xf bank_mask:0xf
	v_perm_b32 v162, v166, v162, v161
	v_perm_b32 v163, v167, v163, v161
	v_perm_b32 v174, v176, v174, v161
	v_perm_b32 v175, v177, v175, v161
	v_cndmask_b32_e32 v168, v163, v162, vcc
	v_cndmask_b32_e32 v178, v175, v174, vcc
	s_nop 1
	v_mov_b32_dpp v169, v168 quad_perm:[2,3,0,1] row_mask:0xf bank_mask:0xf
	v_mov_b32_dpp v179, v178 quad_perm:[2,3,0,1] row_mask:0xf bank_mask:0xf
	v_cndmask_b32_e32 v170, v162, v169, vcc
	v_cndmask_b32_e32 v171, v169, v163, vcc
	v_cndmask_b32_e32 v184, v174, v179, vcc
	v_cndmask_b32_e32 v185, v179, v175, vcc
	global_store_dwordx2 v[156:157], v[170:171], off
	global_store_dwordx2 v[164:165], v[184:185], off
	v_cvt_pk_bf16_f32 v162, v108, v109
	v_cvt_pk_bf16_f32 v163, v110, v111
	v_cvt_pk_bf16_f32 v174, v104, v105
	v_cvt_pk_bf16_f32 v175, v106, v107
	v_mov_b32_dpp v166, v162 quad_perm:[1,0,3,2] row_mask:0xf bank_mask:0xf
	v_mov_b32_dpp v167, v163 quad_perm:[1,0,3,2] row_mask:0xf bank_mask:0xf
	v_mov_b32_dpp v176, v174 quad_perm:[1,0,3,2] row_mask:0xf bank_mask:0xf
	v_mov_b32_dpp v177, v175 quad_perm:[1,0,3,2] row_mask:0xf bank_mask:0xf
	v_perm_b32 v162, v166, v162, v161
	v_perm_b32 v163, v167, v163, v161
	v_perm_b32 v174, v176, v174, v161
	v_perm_b32 v175, v177, v175, v161
	v_cndmask_b32_e32 v168, v163, v162, vcc
	v_cndmask_b32_e32 v178, v175, v174, vcc
	s_nop 1
	v_mov_b32_dpp v169, v168 quad_perm:[2,3,0,1] row_mask:0xf bank_mask:0xf
	v_mov_b32_dpp v179, v178 quad_perm:[2,3,0,1] row_mask:0xf bank_mask:0xf
	v_cndmask_b32_e32 v170, v162, v169, vcc
	v_cndmask_b32_e32 v171, v169, v163, vcc
	v_cndmask_b32_e32 v184, v174, v179, vcc
	v_cndmask_b32_e32 v185, v179, v175, vcc
	global_store_dwordx2 v[172:173], v[170:171], off
	global_store_dwordx2 v[180:181], v[184:185], off
	v_cvt_pk_bf16_f32 v162, v116, v117
	v_cvt_pk_bf16_f32 v163, v118, v119
	v_cvt_pk_bf16_f32 v174, v112, v113
	v_cvt_pk_bf16_f32 v175, v114, v115
	v_mov_b32_dpp v166, v162 quad_perm:[1,0,3,2] row_mask:0xf bank_mask:0xf
	v_mov_b32_dpp v167, v163 quad_perm:[1,0,3,2] row_mask:0xf bank_mask:0xf
	v_mov_b32_dpp v176, v174 quad_perm:[1,0,3,2] row_mask:0xf bank_mask:0xf
	v_mov_b32_dpp v177, v175 quad_perm:[1,0,3,2] row_mask:0xf bank_mask:0xf
	v_perm_b32 v162, v166, v162, v161
	v_perm_b32 v163, v167, v163, v161
	v_perm_b32 v174, v176, v174, v161
	v_perm_b32 v175, v177, v175, v161
	v_cndmask_b32_e32 v168, v163, v162, vcc
	v_cndmask_b32_e32 v178, v175, v174, vcc
	s_nop 1
	v_mov_b32_dpp v169, v168 quad_perm:[2,3,0,1] row_mask:0xf bank_mask:0xf
	v_mov_b32_dpp v179, v178 quad_perm:[2,3,0,1] row_mask:0xf bank_mask:0xf
	v_cndmask_b32_e32 v170, v162, v169, vcc
	v_cndmask_b32_e32 v171, v169, v163, vcc
	v_cndmask_b32_e32 v184, v174, v179, vcc
	v_cndmask_b32_e32 v185, v179, v175, vcc
	global_store_dwordx2 v[156:157], v[170:171], off offset:32
	global_store_dwordx2 v[164:165], v[184:185], off offset:32
	v_cvt_pk_bf16_f32 v162, v92, v93
	v_cvt_pk_bf16_f32 v163, v94, v95
	v_cvt_pk_bf16_f32 v174, v88, v89
	v_cvt_pk_bf16_f32 v175, v90, v91
	v_mov_b32_dpp v166, v162 quad_perm:[1,0,3,2] row_mask:0xf bank_mask:0xf
	v_mov_b32_dpp v167, v163 quad_perm:[1,0,3,2] row_mask:0xf bank_mask:0xf
	v_mov_b32_dpp v176, v174 quad_perm:[1,0,3,2] row_mask:0xf bank_mask:0xf
	v_mov_b32_dpp v177, v175 quad_perm:[1,0,3,2] row_mask:0xf bank_mask:0xf
	v_perm_b32 v162, v166, v162, v161
	v_perm_b32 v163, v167, v163, v161
	v_perm_b32 v174, v176, v174, v161
	v_perm_b32 v175, v177, v175, v161
	v_cndmask_b32_e32 v168, v163, v162, vcc
	v_cndmask_b32_e32 v178, v175, v174, vcc
	s_nop 1
	v_mov_b32_dpp v169, v168 quad_perm:[2,3,0,1] row_mask:0xf bank_mask:0xf
	v_mov_b32_dpp v179, v178 quad_perm:[2,3,0,1] row_mask:0xf bank_mask:0xf
	v_cndmask_b32_e32 v170, v162, v169, vcc
	v_cndmask_b32_e32 v171, v169, v163, vcc
	v_cndmask_b32_e32 v184, v174, v179, vcc
	v_cndmask_b32_e32 v185, v179, v175, vcc
	global_store_dwordx2 v[172:173], v[170:171], off offset:32
	global_store_dwordx2 v[180:181], v[184:185], off offset:32
	v_cvt_pk_bf16_f32 v162, v100, v101
	v_cvt_pk_bf16_f32 v163, v102, v103
	v_cvt_pk_bf16_f32 v174, v96, v97
	v_cvt_pk_bf16_f32 v175, v98, v99
	v_mov_b32_dpp v166, v162 quad_perm:[1,0,3,2] row_mask:0xf bank_mask:0xf
	v_mov_b32_dpp v167, v163 quad_perm:[1,0,3,2] row_mask:0xf bank_mask:0xf
	v_mov_b32_dpp v176, v174 quad_perm:[1,0,3,2] row_mask:0xf bank_mask:0xf
	v_mov_b32_dpp v177, v175 quad_perm:[1,0,3,2] row_mask:0xf bank_mask:0xf
	v_perm_b32 v162, v166, v162, v161
	v_perm_b32 v163, v167, v163, v161
	v_perm_b32 v174, v176, v174, v161
	v_perm_b32 v175, v177, v175, v161
	v_cndmask_b32_e32 v168, v163, v162, vcc
	v_cndmask_b32_e32 v178, v175, v174, vcc
	s_nop 1
	v_mov_b32_dpp v169, v168 quad_perm:[2,3,0,1] row_mask:0xf bank_mask:0xf
	v_mov_b32_dpp v179, v178 quad_perm:[2,3,0,1] row_mask:0xf bank_mask:0xf
	v_cndmask_b32_e32 v170, v162, v169, vcc
	v_cndmask_b32_e32 v171, v169, v163, vcc
	v_cndmask_b32_e32 v184, v174, v179, vcc
	v_cndmask_b32_e32 v185, v179, v175, vcc
	global_store_dwordx2 v[156:157], v[170:171], off offset:64
	global_store_dwordx2 v[164:165], v[184:185], off offset:64
	v_cvt_pk_bf16_f32 v162, v76, v77
	v_cvt_pk_bf16_f32 v163, v78, v79
	v_cvt_pk_bf16_f32 v174, v72, v73
	v_cvt_pk_bf16_f32 v175, v74, v75
	v_mov_b32_dpp v166, v162 quad_perm:[1,0,3,2] row_mask:0xf bank_mask:0xf
	v_mov_b32_dpp v167, v163 quad_perm:[1,0,3,2] row_mask:0xf bank_mask:0xf
	v_mov_b32_dpp v176, v174 quad_perm:[1,0,3,2] row_mask:0xf bank_mask:0xf
	v_mov_b32_dpp v177, v175 quad_perm:[1,0,3,2] row_mask:0xf bank_mask:0xf
	v_perm_b32 v162, v166, v162, v161
	v_perm_b32 v163, v167, v163, v161
	v_perm_b32 v174, v176, v174, v161
	v_perm_b32 v175, v177, v175, v161
	v_cndmask_b32_e32 v168, v163, v162, vcc
	v_cndmask_b32_e32 v178, v175, v174, vcc
	s_nop 1
	v_mov_b32_dpp v169, v168 quad_perm:[2,3,0,1] row_mask:0xf bank_mask:0xf
	v_mov_b32_dpp v179, v178 quad_perm:[2,3,0,1] row_mask:0xf bank_mask:0xf
	v_cndmask_b32_e32 v170, v162, v169, vcc
	v_cndmask_b32_e32 v171, v169, v163, vcc
	v_cndmask_b32_e32 v184, v174, v179, vcc
	v_cndmask_b32_e32 v185, v179, v175, vcc
	global_store_dwordx2 v[172:173], v[170:171], off offset:64
	global_store_dwordx2 v[180:181], v[184:185], off offset:64
	v_cvt_pk_bf16_f32 v162, v84, v85
	v_cvt_pk_bf16_f32 v163, v86, v87
	v_cvt_pk_bf16_f32 v174, v80, v81
	v_cvt_pk_bf16_f32 v175, v82, v83
	v_mov_b32_dpp v166, v162 quad_perm:[1,0,3,2] row_mask:0xf bank_mask:0xf
	v_mov_b32_dpp v167, v163 quad_perm:[1,0,3,2] row_mask:0xf bank_mask:0xf
	v_mov_b32_dpp v176, v174 quad_perm:[1,0,3,2] row_mask:0xf bank_mask:0xf
	v_mov_b32_dpp v177, v175 quad_perm:[1,0,3,2] row_mask:0xf bank_mask:0xf
	v_perm_b32 v162, v166, v162, v161
	v_perm_b32 v163, v167, v163, v161
	v_perm_b32 v174, v176, v174, v161
	v_perm_b32 v175, v177, v175, v161
	v_cndmask_b32_e32 v168, v163, v162, vcc
	v_cndmask_b32_e32 v178, v175, v174, vcc
	s_nop 1
	v_mov_b32_dpp v169, v168 quad_perm:[2,3,0,1] row_mask:0xf bank_mask:0xf
	v_mov_b32_dpp v179, v178 quad_perm:[2,3,0,1] row_mask:0xf bank_mask:0xf
	v_cndmask_b32_e32 v170, v162, v169, vcc
	v_cndmask_b32_e32 v171, v169, v163, vcc
	v_cndmask_b32_e32 v184, v174, v179, vcc
	v_cndmask_b32_e32 v185, v179, v175, vcc
	global_store_dwordx2 v[156:157], v[170:171], off offset:96
	global_store_dwordx2 v[164:165], v[184:185], off offset:96
	v_cvt_pk_bf16_f32 v162, v68, v69
	v_cvt_pk_bf16_f32 v163, v70, v71
	v_cvt_pk_bf16_f32 v174, v64, v65
	v_cvt_pk_bf16_f32 v175, v66, v67
	v_mov_b32_dpp v166, v162 quad_perm:[1,0,3,2] row_mask:0xf bank_mask:0xf
	v_mov_b32_dpp v167, v163 quad_perm:[1,0,3,2] row_mask:0xf bank_mask:0xf
	v_mov_b32_dpp v176, v174 quad_perm:[1,0,3,2] row_mask:0xf bank_mask:0xf
	v_mov_b32_dpp v177, v175 quad_perm:[1,0,3,2] row_mask:0xf bank_mask:0xf
	v_perm_b32 v162, v166, v162, v161
	v_perm_b32 v163, v167, v163, v161
	v_perm_b32 v174, v176, v174, v161
	v_perm_b32 v175, v177, v175, v161
	v_cndmask_b32_e32 v168, v163, v162, vcc
	v_cndmask_b32_e32 v178, v175, v174, vcc
	s_nop 1
	v_mov_b32_dpp v169, v168 quad_perm:[2,3,0,1] row_mask:0xf bank_mask:0xf
	v_mov_b32_dpp v179, v178 quad_perm:[2,3,0,1] row_mask:0xf bank_mask:0xf
	v_cndmask_b32_e32 v170, v162, v169, vcc
	v_cndmask_b32_e32 v171, v169, v163, vcc
	v_cndmask_b32_e32 v184, v174, v179, vcc
	v_cndmask_b32_e32 v185, v179, v175, vcc
	global_store_dwordx2 v[172:173], v[170:171], off offset:96
	global_store_dwordx2 v[180:181], v[184:185], off offset:96
	v_cvt_pk_bf16_f32 v162, v60, v61
	v_cvt_pk_bf16_f32 v163, v62, v63
	v_cvt_pk_bf16_f32 v174, v56, v57
	v_cvt_pk_bf16_f32 v175, v58, v59
	v_mov_b32_dpp v166, v162 quad_perm:[1,0,3,2] row_mask:0xf bank_mask:0xf
	v_mov_b32_dpp v167, v163 quad_perm:[1,0,3,2] row_mask:0xf bank_mask:0xf
	v_mov_b32_dpp v176, v174 quad_perm:[1,0,3,2] row_mask:0xf bank_mask:0xf
	v_mov_b32_dpp v177, v175 quad_perm:[1,0,3,2] row_mask:0xf bank_mask:0xf
	v_perm_b32 v162, v166, v162, v161
	v_perm_b32 v163, v167, v163, v161
	v_perm_b32 v174, v176, v174, v161
	v_perm_b32 v175, v177, v175, v161
	v_cndmask_b32_e32 v168, v163, v162, vcc
	v_cndmask_b32_e32 v178, v175, v174, vcc
	s_nop 1
	v_mov_b32_dpp v169, v168 quad_perm:[2,3,0,1] row_mask:0xf bank_mask:0xf
	v_mov_b32_dpp v179, v178 quad_perm:[2,3,0,1] row_mask:0xf bank_mask:0xf
	v_cndmask_b32_e32 v170, v162, v169, vcc
	v_cndmask_b32_e32 v171, v169, v163, vcc
	v_cndmask_b32_e32 v184, v174, v179, vcc
	v_cndmask_b32_e32 v185, v179, v175, vcc
	global_store_dwordx2 v[156:157], v[170:171], off offset:256
	global_store_dwordx2 v[164:165], v[184:185], off offset:256
	v_cvt_pk_bf16_f32 v162, v44, v45
	v_cvt_pk_bf16_f32 v163, v46, v47
	v_cvt_pk_bf16_f32 v174, v40, v41
	v_cvt_pk_bf16_f32 v175, v42, v43
	v_mov_b32_dpp v166, v162 quad_perm:[1,0,3,2] row_mask:0xf bank_mask:0xf
	v_mov_b32_dpp v167, v163 quad_perm:[1,0,3,2] row_mask:0xf bank_mask:0xf
	v_mov_b32_dpp v176, v174 quad_perm:[1,0,3,2] row_mask:0xf bank_mask:0xf
	v_mov_b32_dpp v177, v175 quad_perm:[1,0,3,2] row_mask:0xf bank_mask:0xf
	v_perm_b32 v162, v166, v162, v161
	v_perm_b32 v163, v167, v163, v161
	v_perm_b32 v174, v176, v174, v161
	v_perm_b32 v175, v177, v175, v161
	v_cndmask_b32_e32 v168, v163, v162, vcc
	v_cndmask_b32_e32 v178, v175, v174, vcc
	s_nop 1
	v_mov_b32_dpp v169, v168 quad_perm:[2,3,0,1] row_mask:0xf bank_mask:0xf
	v_mov_b32_dpp v179, v178 quad_perm:[2,3,0,1] row_mask:0xf bank_mask:0xf
	v_cndmask_b32_e32 v170, v162, v169, vcc
	v_cndmask_b32_e32 v171, v169, v163, vcc
	v_cndmask_b32_e32 v184, v174, v179, vcc
	v_cndmask_b32_e32 v185, v179, v175, vcc
	global_store_dwordx2 v[172:173], v[170:171], off offset:256
	global_store_dwordx2 v[180:181], v[184:185], off offset:256
	v_cvt_pk_bf16_f32 v162, v52, v53
	v_cvt_pk_bf16_f32 v163, v54, v55
	v_cvt_pk_bf16_f32 v174, v48, v49
	v_cvt_pk_bf16_f32 v175, v50, v51
	v_mov_b32_dpp v166, v162 quad_perm:[1,0,3,2] row_mask:0xf bank_mask:0xf
	v_mov_b32_dpp v167, v163 quad_perm:[1,0,3,2] row_mask:0xf bank_mask:0xf
	v_mov_b32_dpp v176, v174 quad_perm:[1,0,3,2] row_mask:0xf bank_mask:0xf
	v_mov_b32_dpp v177, v175 quad_perm:[1,0,3,2] row_mask:0xf bank_mask:0xf
	v_perm_b32 v162, v166, v162, v161
	v_perm_b32 v163, v167, v163, v161
	v_perm_b32 v174, v176, v174, v161
	v_perm_b32 v175, v177, v175, v161
	v_cndmask_b32_e32 v168, v163, v162, vcc
	v_cndmask_b32_e32 v178, v175, v174, vcc
	s_nop 1
	v_mov_b32_dpp v169, v168 quad_perm:[2,3,0,1] row_mask:0xf bank_mask:0xf
	v_mov_b32_dpp v179, v178 quad_perm:[2,3,0,1] row_mask:0xf bank_mask:0xf
	v_cndmask_b32_e32 v170, v162, v169, vcc
	v_cndmask_b32_e32 v171, v169, v163, vcc
	v_cndmask_b32_e32 v184, v174, v179, vcc
	v_cndmask_b32_e32 v185, v179, v175, vcc
	global_store_dwordx2 v[156:157], v[170:171], off offset:288
	global_store_dwordx2 v[164:165], v[184:185], off offset:288
	v_cvt_pk_bf16_f32 v162, v28, v29
	v_cvt_pk_bf16_f32 v163, v30, v31
	v_cvt_pk_bf16_f32 v174, v24, v25
	v_cvt_pk_bf16_f32 v175, v26, v27
	v_mov_b32_dpp v166, v162 quad_perm:[1,0,3,2] row_mask:0xf bank_mask:0xf
	v_mov_b32_dpp v167, v163 quad_perm:[1,0,3,2] row_mask:0xf bank_mask:0xf
	v_mov_b32_dpp v176, v174 quad_perm:[1,0,3,2] row_mask:0xf bank_mask:0xf
	v_mov_b32_dpp v177, v175 quad_perm:[1,0,3,2] row_mask:0xf bank_mask:0xf
	v_perm_b32 v162, v166, v162, v161
	v_perm_b32 v163, v167, v163, v161
	v_perm_b32 v174, v176, v174, v161
	v_perm_b32 v175, v177, v175, v161
	v_cndmask_b32_e32 v168, v163, v162, vcc
	v_cndmask_b32_e32 v178, v175, v174, vcc
	s_nop 1
	v_mov_b32_dpp v169, v168 quad_perm:[2,3,0,1] row_mask:0xf bank_mask:0xf
	v_mov_b32_dpp v179, v178 quad_perm:[2,3,0,1] row_mask:0xf bank_mask:0xf
	v_cndmask_b32_e32 v170, v162, v169, vcc
	v_cndmask_b32_e32 v171, v169, v163, vcc
	v_cndmask_b32_e32 v184, v174, v179, vcc
	v_cndmask_b32_e32 v185, v179, v175, vcc
	global_store_dwordx2 v[172:173], v[170:171], off offset:288
	global_store_dwordx2 v[180:181], v[184:185], off offset:288
	v_cvt_pk_bf16_f32 v162, v36, v37
	v_cvt_pk_bf16_f32 v163, v38, v39
	v_cvt_pk_bf16_f32 v174, v32, v33
	v_cvt_pk_bf16_f32 v175, v34, v35
	v_mov_b32_dpp v166, v162 quad_perm:[1,0,3,2] row_mask:0xf bank_mask:0xf
	v_mov_b32_dpp v167, v163 quad_perm:[1,0,3,2] row_mask:0xf bank_mask:0xf
	v_mov_b32_dpp v176, v174 quad_perm:[1,0,3,2] row_mask:0xf bank_mask:0xf
	v_mov_b32_dpp v177, v175 quad_perm:[1,0,3,2] row_mask:0xf bank_mask:0xf
	v_perm_b32 v162, v166, v162, v161
	v_perm_b32 v163, v167, v163, v161
	v_perm_b32 v174, v176, v174, v161
	v_perm_b32 v175, v177, v175, v161
	v_cndmask_b32_e32 v168, v163, v162, vcc
	v_cndmask_b32_e32 v178, v175, v174, vcc
	s_nop 1
	v_mov_b32_dpp v169, v168 quad_perm:[2,3,0,1] row_mask:0xf bank_mask:0xf
	v_mov_b32_dpp v179, v178 quad_perm:[2,3,0,1] row_mask:0xf bank_mask:0xf
	v_cndmask_b32_e32 v170, v162, v169, vcc
	v_cndmask_b32_e32 v171, v169, v163, vcc
	v_cndmask_b32_e32 v184, v174, v179, vcc
	v_cndmask_b32_e32 v185, v179, v175, vcc
	global_store_dwordx2 v[156:157], v[170:171], off offset:320
	global_store_dwordx2 v[164:165], v[184:185], off offset:320
	v_cvt_pk_bf16_f32 v162, v12, v13
	v_cvt_pk_bf16_f32 v163, v14, v15
	v_cvt_pk_bf16_f32 v174, v8, v9
	v_cvt_pk_bf16_f32 v175, v10, v11
	v_mov_b32_dpp v166, v162 quad_perm:[1,0,3,2] row_mask:0xf bank_mask:0xf
	v_mov_b32_dpp v167, v163 quad_perm:[1,0,3,2] row_mask:0xf bank_mask:0xf
	v_mov_b32_dpp v176, v174 quad_perm:[1,0,3,2] row_mask:0xf bank_mask:0xf
	v_mov_b32_dpp v177, v175 quad_perm:[1,0,3,2] row_mask:0xf bank_mask:0xf
	v_perm_b32 v162, v166, v162, v161
	v_perm_b32 v163, v167, v163, v161
	v_perm_b32 v174, v176, v174, v161
	v_perm_b32 v175, v177, v175, v161
	v_cndmask_b32_e32 v168, v163, v162, vcc
	v_cndmask_b32_e32 v178, v175, v174, vcc
	s_nop 1
	v_mov_b32_dpp v169, v168 quad_perm:[2,3,0,1] row_mask:0xf bank_mask:0xf
	v_mov_b32_dpp v179, v178 quad_perm:[2,3,0,1] row_mask:0xf bank_mask:0xf
	v_cndmask_b32_e32 v170, v162, v169, vcc
	v_cndmask_b32_e32 v171, v169, v163, vcc
	v_cndmask_b32_e32 v184, v174, v179, vcc
	v_cndmask_b32_e32 v185, v179, v175, vcc
	global_store_dwordx2 v[172:173], v[170:171], off offset:320
	global_store_dwordx2 v[180:181], v[184:185], off offset:320
	v_cvt_pk_bf16_f32 v162, v20, v21
	v_cvt_pk_bf16_f32 v163, v22, v23
	v_cvt_pk_bf16_f32 v174, v16, v17
	v_cvt_pk_bf16_f32 v175, v18, v19
	v_mov_b32_dpp v166, v162 quad_perm:[1,0,3,2] row_mask:0xf bank_mask:0xf
	v_mov_b32_dpp v167, v163 quad_perm:[1,0,3,2] row_mask:0xf bank_mask:0xf
	v_mov_b32_dpp v176, v174 quad_perm:[1,0,3,2] row_mask:0xf bank_mask:0xf
	v_mov_b32_dpp v177, v175 quad_perm:[1,0,3,2] row_mask:0xf bank_mask:0xf
	v_perm_b32 v162, v166, v162, v161
	v_perm_b32 v163, v167, v163, v161
	v_perm_b32 v174, v176, v174, v161
	v_perm_b32 v175, v177, v175, v161
	v_cndmask_b32_e32 v168, v163, v162, vcc
	v_cndmask_b32_e32 v178, v175, v174, vcc
	s_nop 1
	v_mov_b32_dpp v169, v168 quad_perm:[2,3,0,1] row_mask:0xf bank_mask:0xf
	v_mov_b32_dpp v179, v178 quad_perm:[2,3,0,1] row_mask:0xf bank_mask:0xf
	v_cndmask_b32_e32 v170, v162, v169, vcc
	v_cndmask_b32_e32 v171, v169, v163, vcc
	v_cndmask_b32_e32 v184, v174, v179, vcc
	v_cndmask_b32_e32 v185, v179, v175, vcc
	global_store_dwordx2 v[156:157], v[170:171], off offset:352
	global_store_dwordx2 v[164:165], v[184:185], off offset:352
	v_cvt_pk_bf16_f32 v162, v4, v5
	v_cvt_pk_bf16_f32 v163, v6, v7
	v_cvt_pk_bf16_f32 v174, v0, v1
	v_cvt_pk_bf16_f32 v175, v2, v3
	v_mov_b32_dpp v166, v162 quad_perm:[1,0,3,2] row_mask:0xf bank_mask:0xf
	v_mov_b32_dpp v167, v163 quad_perm:[1,0,3,2] row_mask:0xf bank_mask:0xf
	v_mov_b32_dpp v176, v174 quad_perm:[1,0,3,2] row_mask:0xf bank_mask:0xf
	v_mov_b32_dpp v177, v175 quad_perm:[1,0,3,2] row_mask:0xf bank_mask:0xf
	v_perm_b32 v162, v166, v162, v161
	v_perm_b32 v163, v167, v163, v161
	v_perm_b32 v174, v176, v174, v161
	v_perm_b32 v175, v177, v175, v161
	v_cndmask_b32_e32 v168, v163, v162, vcc
	v_cndmask_b32_e32 v178, v175, v174, vcc
	s_nop 1
	v_mov_b32_dpp v169, v168 quad_perm:[2,3,0,1] row_mask:0xf bank_mask:0xf
	v_mov_b32_dpp v179, v178 quad_perm:[2,3,0,1] row_mask:0xf bank_mask:0xf
	v_cndmask_b32_e32 v170, v162, v169, vcc
	v_cndmask_b32_e32 v171, v169, v163, vcc
	v_cndmask_b32_e32 v184, v174, v179, vcc
	v_cndmask_b32_e32 v185, v179, v175, vcc
	global_store_dwordx2 v[172:173], v[170:171], off offset:352
	global_store_dwordx2 v[180:181], v[184:185], off offset:352
